# v78 + HGRN2: next chunk's eight log-f row loads issued right after the cumsum barrier (registers dead there) instead of in the end-of-step-2 burst
# speedup vs baseline: 1.0140x; 1.0013x over previous
.LBB0_1169:
	s_waitcnt vmcnt(5)
	v_pk_add_f32 v[118:119], v[92:93], 0 op_sel_hi:[1,0]
	v_add_u32_e32 v58, s18, v132
	v_pk_add_f32 v[116:117], v[118:119], v[80:81]
	v_add_u32_e32 v160, 0, v132
	v_pk_add_f32 v[114:115], v[116:117], v[82:83]
	v_readlane_b32 s6, v254, 20
	v_pk_add_f32 v[112:113], v[114:115], v[86:87]
	v_readlane_b32 s7, v254, 21
	v_pk_add_f32 v[110:111], v[112:113], v[90:91]
	s_andn2_b64 vcc, exec, s[6:7]
	v_pk_add_f32 v[108:109], v[110:111], v[96:97]
	s_mov_b64 s[6:7], -1
	v_pk_add_f32 v[106:107], v[108:109], v[100:101]
	s_nop 0
	v_pk_add_f32 v[104:105], v[106:107], v[102:103]
	ds_write_b64 v58, v[104:105]
	v_add_u32_e32 v58, 0x20a00, v160
	s_waitcnt lgkmcnt(0)
	s_barrier
	ds_read2st64_b64 v[70:73], v58 offset1:1
	ds_read2st64_b64 v[66:69], v58 offset0:2 offset1:3
	ds_read2st64_b64 v[62:65], v58 offset0:4 offset1:5
	ds_read2st64_b64 v[58:61], v58 offset0:6 offset1:7
	s_cmp_eq_u32 s2, 31
	s_cbranch_scc1 .Lhg_nolf
	s_add_i32 s8, s2, 1
	s_lshl_b32 s8, s8, 6
	s_mov_b32 s9, s37
	s_lshl_b64 s[10:11], s[8:9], 13
	v_lshl_add_u64 v[238:239], v[76:77], 0, s[10:11]
	global_load_dwordx2 v[92:93], v[238:239], off nt
	s_add_u32 s10, s10, 0x2000
	s_addc_u32 s11, s11, 0
	v_lshl_add_u64 v[238:239], v[76:77], 0, s[10:11]
	global_load_dwordx2 v[80:81], v[238:239], off nt
	s_add_u32 s10, s10, 0x2000
	s_addc_u32 s11, s11, 0
	v_lshl_add_u64 v[238:239], v[76:77], 0, s[10:11]
	global_load_dwordx2 v[82:83], v[238:239], off nt
	s_add_u32 s10, s10, 0x2000
	s_addc_u32 s11, s11, 0
	v_lshl_add_u64 v[238:239], v[76:77], 0, s[10:11]
	global_load_dwordx2 v[86:87], v[238:239], off nt
	s_add_u32 s10, s10, 0x2000
	s_addc_u32 s11, s11, 0
	v_lshl_add_u64 v[238:239], v[76:77], 0, s[10:11]
	global_load_dwordx2 v[90:91], v[238:239], off nt
	s_add_u32 s10, s10, 0x2000
	s_addc_u32 s11, s11, 0
	v_lshl_add_u64 v[238:239], v[76:77], 0, s[10:11]
	global_load_dwordx2 v[96:97], v[238:239], off nt
	s_add_u32 s10, s10, 0x2000
	s_addc_u32 s11, s11, 0
	v_lshl_add_u64 v[238:239], v[76:77], 0, s[10:11]
	global_load_dwordx2 v[100:101], v[238:239], off nt
	s_add_u32 s10, s10, 0x2000
	s_addc_u32 s11, s11, 0
	v_lshl_add_u64 v[238:239], v[76:77], 0, s[10:11]
	global_load_dwordx2 v[102:103], v[238:239], off nt
.Lhg_nolf:
	s_waitcnt lgkmcnt(3)
	v_pk_add_f32 v[122:123], v[70:71], 0 op_sel_hi:[1,0]
	s_nop 0
	v_pk_add_f32 v[70:71], v[122:123], v[72:73]
	s_waitcnt lgkmcnt(2)
	v_pk_add_f32 v[70:71], v[70:71], v[66:67]
	s_nop 0
	v_pk_add_f32 v[70:71], v[70:71], v[68:69]
	s_waitcnt lgkmcnt(1)
	v_pk_add_f32 v[120:121], v[70:71], v[62:63]
	s_nop 0
	v_pk_add_f32 v[120:121], v[120:121], v[64:65]
	s_waitcnt lgkmcnt(0)
	v_pk_add_f32 v[120:121], v[120:121], v[58:59]
	s_nop 0
	v_pk_add_f32 v[120:121], v[120:121], v[60:61]
	s_cbranch_vccnz .LBB0_1171
	s_mov_b64 s[6:7], 0

.LBB0_1173:
	v_readlane_b32 s6, v254, 18
	v_readlane_b32 s7, v254, 19
	s_mul_i32 s3, s20, 0x880
	s_nop 0
	v_cndmask_b32_e64 v123, v123, 0, s[6:7]
	v_cndmask_b32_e64 v122, v122, 0, s[6:7]
	v_readlane_b32 s6, v254, 26
	v_pk_add_f32 v[72:73], v[72:73], v[122:123]
	v_readlane_b32 s7, v254, 27
	s_nop 1
	v_cndmask_b32_e64 v73, v123, v73, s[6:7]
	v_cndmask_b32_e64 v72, v122, v72, s[6:7]
	v_readlane_b32 s6, v254, 28
	v_pk_add_f32 v[66:67], v[66:67], v[72:73]
	v_readlane_b32 s7, v254, 29
	s_nop 1
	v_cndmask_b32_e64 v67, v73, v67, s[6:7]
	v_cndmask_b32_e64 v66, v72, v66, s[6:7]
	v_readlane_b32 s6, v254, 30
	v_pk_add_f32 v[68:69], v[68:69], v[66:67]
	v_readlane_b32 s7, v254, 31
	s_nop 1
	v_cndmask_b32_e64 v67, v67, v69, s[6:7]
	v_cndmask_b32_e64 v66, v66, v68, s[6:7]
	v_readlane_b32 s6, v254, 32
	v_pk_add_f32 v[62:63], v[62:63], v[66:67]
	v_readlane_b32 s7, v254, 33
	v_and_b32_e32 v69, 0xffff0000, v125
	v_lshlrev_b32_e32 v68, 16, v125
	v_cndmask_b32_e64 v63, v67, v63, s[6:7]
	v_cndmask_b32_e64 v62, v66, v62, s[6:7]
	v_readlane_b32 s6, v254, 34
	v_pk_add_f32 v[64:65], v[64:65], v[62:63]
	v_readlane_b32 s7, v254, 35
	v_lshlrev_b32_e32 v66, 16, v75
	v_and_b32_e32 v67, 0xffff0000, v75
	v_cndmask_b32_e64 v63, v63, v65, s[6:7]
	v_cndmask_b32_e64 v62, v62, v64, s[6:7]
	v_readlane_b32 s6, v254, 36
	v_pk_add_f32 v[58:59], v[58:59], v[62:63]
	v_readlane_b32 s7, v254, 37
	s_nop 1
	v_cndmask_b32_e64 v59, v63, v59, s[6:7]
	v_cndmask_b32_e64 v58, v62, v58, s[6:7]
	v_readlane_b32 s6, v254, 40
	v_pk_add_f32 v[60:61], v[60:61], v[58:59]
	v_readlane_b32 s7, v254, 41
	s_nop 1
	v_cndmask_b32_e64 v58, v58, v60, s[6:7]
	v_sub_f32_e32 v60, v120, v70
	v_cndmask_b32_e64 v59, v59, v61, s[6:7]
	v_exp_f32_e32 v64, v60
	v_sub_f32_e32 v60, v121, v71
	v_exp_f32_e32 v65, v60
	v_pk_add_f32 v[60:61], v[118:119], v[58:59]
	s_nop 0
	v_pk_add_f32 v[62:63], v[60:61], v[70:71] neg_lo:[0,1] neg_hi:[0,1]
	v_exp_f32_e32 v60, v60
	v_min_f32_e32 v73, 0x42e60000, v63
	v_min_f32_e64 v63, -v63, s14
	v_min_f32_e32 v72, 0x42e60000, v62
	v_min_f32_e64 v62, -v62, s14
	v_exp_f32_e32 v63, v63
	v_exp_f32_e32 v72, v72
	v_exp_f32_e32 v73, v73
	v_exp_f32_e32 v62, v62
	v_exp_f32_e32 v61, v61
	v_mul_f32_e32 v63, v63, v69
	v_add_u32_e32 v69, s3, v0
	v_mul_f32_e32 v60, v60, v66
	v_mul_f32_e32 v72, v72, v66
	v_mul_f32_e32 v73, v73, v67
	v_mul_f32_e32 v62, v62, v68
	v_cvt_pk_bf16_f32 v68, v72, v73
	ds_write_b32 v69, v68
	v_mul_f32_e32 v61, v61, v67
	v_cvt_pk_bf16_f32 v60, v60, v61
	ds_write_b32 v69, v60 offset:17408
	v_cvt_pk_bf16_f32 v60, v62, v63
	ds_write_b32 v69, v60 offset:34816
	v_pk_add_f32 v[60:61], v[116:117], v[58:59]
	v_mul_f32_e32 v66, v64, v62
	v_mul_f32_e32 v67, v63, v65
	v_pk_add_f32 v[62:63], v[60:61], v[70:71] neg_lo:[0,1] neg_hi:[0,1]
	v_exp_f32_e32 v60, v60
	v_min_f32_e32 v117, 0x42e60000, v62
	v_min_f32_e32 v118, 0x42e60000, v63
	v_min_f32_e64 v62, -v62, s14
	v_exp_f32_e32 v117, v117
	v_exp_f32_e32 v118, v118
	v_exp_f32_e32 v62, v62
	v_min_f32_e64 v63, -v63, s14
	v_exp_f32_e32 v61, v61
	v_exp_f32_e32 v63, v63
	v_lshlrev_b32_e32 v68, 16, v126
	v_and_b32_e32 v72, 0xffff0000, v126
	v_lshlrev_b32_e32 v73, 16, v127
	v_mul_f32_e32 v60, v60, v68
	v_and_b32_e32 v116, 0xffff0000, v127
	v_mul_f32_e32 v117, v117, v68
	v_mul_f32_e32 v118, v118, v72
	v_mul_f32_e32 v62, v62, v73
	v_cvt_pk_bf16_f32 v73, v117, v118
	ds_write_b32 v69, v73 offset:272
	v_mul_f32_e32 v61, v61, v72
	v_cvt_pk_bf16_f32 v60, v60, v61
	v_mul_f32_e32 v63, v63, v116
	ds_write_b32 v69, v60 offset:17680
	v_cvt_pk_bf16_f32 v60, v62, v63
	ds_write_b32 v69, v60 offset:35088
	v_pk_add_f32 v[60:61], v[114:115], v[58:59]
	v_mul_f32_e32 v68, v64, v62
	v_mul_f32_e32 v72, v63, v65
	v_pk_add_f32 v[62:63], v[60:61], v[70:71] neg_lo:[0,1] neg_hi:[0,1]
	v_exp_f32_e32 v60, v60
	v_min_f32_e32 v117, 0x42e60000, v62
	v_min_f32_e32 v118, 0x42e60000, v63
	v_min_f32_e64 v62, -v62, s14
	v_exp_f32_e32 v117, v117
	v_exp_f32_e32 v118, v118
	v_exp_f32_e32 v62, v62
	v_min_f32_e64 v63, -v63, s14
	v_exp_f32_e32 v61, v61
	v_exp_f32_e32 v63, v63
	v_lshlrev_b32_e32 v73, 16, v128
	v_and_b32_e32 v114, 0xffff0000, v128
	v_lshlrev_b32_e32 v115, 16, v129
	v_mul_f32_e32 v60, v60, v73
	v_and_b32_e32 v116, 0xffff0000, v129
	v_mul_f32_e32 v117, v117, v73
	v_mul_f32_e32 v118, v118, v114
	v_mul_f32_e32 v62, v62, v115
	v_cvt_pk_bf16_f32 v115, v117, v118
	ds_write_b32 v69, v115 offset:544
	v_mul_f32_e32 v61, v61, v114
	v_cvt_pk_bf16_f32 v60, v60, v61
	v_mul_f32_e32 v63, v63, v116
	ds_write_b32 v69, v60 offset:17952
	v_cvt_pk_bf16_f32 v60, v62, v63
	ds_write_b32 v69, v60 offset:35360
	v_pk_add_f32 v[60:61], v[112:113], v[58:59]
	v_mul_f32_e32 v73, v64, v62
	v_mul_f32_e32 v114, v63, v65
	v_pk_add_f32 v[62:63], v[60:61], v[70:71] neg_lo:[0,1] neg_hi:[0,1]
	v_exp_f32_e32 v60, v60
	v_min_f32_e32 v117, 0x42e60000, v62
	v_min_f32_e32 v118, 0x42e60000, v63
	v_min_f32_e64 v62, -v62, s14
	v_exp_f32_e32 v117, v117
	v_exp_f32_e32 v118, v118
	v_exp_f32_e32 v62, v62
	v_min_f32_e64 v63, -v63, s14
	v_exp_f32_e32 v61, v61
	v_exp_f32_e32 v63, v63
	v_lshlrev_b32_e32 v112, 16, v130
	v_and_b32_e32 v113, 0xffff0000, v130
	v_lshlrev_b32_e32 v115, 16, v131
	v_mul_f32_e32 v60, v60, v112
	v_and_b32_e32 v116, 0xffff0000, v131
	v_mul_f32_e32 v117, v117, v112
	v_mul_f32_e32 v118, v118, v113
	v_mul_f32_e32 v62, v62, v115
	v_cvt_pk_bf16_f32 v115, v117, v118
	ds_write_b32 v69, v115 offset:816
	v_mul_f32_e32 v61, v61, v113
	v_cvt_pk_bf16_f32 v60, v60, v61
	v_mul_f32_e32 v63, v63, v116
	ds_write_b32 v69, v60 offset:18224
	v_cvt_pk_bf16_f32 v60, v62, v63
	ds_write_b32 v69, v60 offset:35632
	v_pk_add_f32 v[60:61], v[110:111], v[58:59]
	v_mul_f32_e32 v112, v64, v62
	v_mul_f32_e32 v113, v63, v65
	v_pk_add_f32 v[62:63], v[60:61], v[70:71] neg_lo:[0,1] neg_hi:[0,1]
	v_exp_f32_e32 v60, v60
	v_min_f32_e32 v117, 0x42e60000, v62
	v_min_f32_e32 v118, 0x42e60000, v63
	v_min_f32_e64 v62, -v62, s14
	v_exp_f32_e32 v117, v117
	v_exp_f32_e32 v118, v118
	v_exp_f32_e32 v62, v62
	v_min_f32_e64 v63, -v63, s14
	v_exp_f32_e32 v61, v61
	v_exp_f32_e32 v63, v63
	v_lshlrev_b32_e32 v110, 16, v140
	v_and_b32_e32 v111, 0xffff0000, v140
	v_lshlrev_b32_e32 v115, 16, v142
	v_mul_f32_e32 v60, v60, v110
	v_and_b32_e32 v116, 0xffff0000, v142
	v_mul_f32_e32 v117, v117, v110
	v_mul_f32_e32 v118, v118, v111
	v_mul_f32_e32 v62, v62, v115
	v_cvt_pk_bf16_f32 v115, v117, v118
	ds_write_b32 v69, v115 offset:1088
	v_mul_f32_e32 v61, v61, v111
	v_cvt_pk_bf16_f32 v60, v60, v61
	v_mul_f32_e32 v63, v63, v116
	ds_write_b32 v69, v60 offset:18496
	v_cvt_pk_bf16_f32 v60, v62, v63
	ds_write_b32 v69, v60 offset:35904
	v_pk_add_f32 v[60:61], v[108:109], v[58:59]
	v_mul_f32_e32 v110, v64, v62
	v_mul_f32_e32 v111, v63, v65
	v_pk_add_f32 v[62:63], v[60:61], v[70:71] neg_lo:[0,1] neg_hi:[0,1]
	v_exp_f32_e32 v60, v60
	v_min_f32_e32 v117, 0x42e60000, v62
	v_min_f32_e32 v118, 0x42e60000, v63
	v_min_f32_e64 v62, -v62, s14
	v_exp_f32_e32 v117, v117
	v_exp_f32_e32 v118, v118
	v_exp_f32_e32 v62, v62
	v_min_f32_e64 v63, -v63, s14
	v_exp_f32_e32 v61, v61
	v_exp_f32_e32 v63, v63
	v_lshlrev_b32_e32 v108, 16, v144
	v_and_b32_e32 v109, 0xffff0000, v144
	v_lshlrev_b32_e32 v115, 16, v149
	v_mul_f32_e32 v60, v60, v108
	v_and_b32_e32 v116, 0xffff0000, v149
	v_mul_f32_e32 v117, v117, v108
	v_mul_f32_e32 v118, v118, v109
	v_mul_f32_e32 v62, v62, v115
	v_cvt_pk_bf16_f32 v115, v117, v118
	ds_write_b32 v69, v115 offset:1360
	v_mul_f32_e32 v61, v61, v109
	v_cvt_pk_bf16_f32 v60, v60, v61
	v_mul_f32_e32 v63, v63, v116
	ds_write_b32 v69, v60 offset:18768
	v_cvt_pk_bf16_f32 v60, v62, v63
	ds_write_b32 v69, v60 offset:36176
	v_pk_add_f32 v[60:61], v[106:107], v[58:59]
	v_mul_f32_e32 v108, v64, v62
	v_mul_f32_e32 v109, v63, v65
	v_pk_add_f32 v[62:63], v[60:61], v[70:71] neg_lo:[0,1] neg_hi:[0,1]
	v_exp_f32_e32 v60, v60
	v_min_f32_e32 v117, 0x42e60000, v62
	v_min_f32_e32 v118, 0x42e60000, v63
	v_min_f32_e64 v62, -v62, s14
	v_exp_f32_e32 v117, v117
	v_exp_f32_e32 v118, v118
	v_exp_f32_e32 v62, v62
	v_min_f32_e64 v63, -v63, s14
	v_exp_f32_e32 v61, v61
	v_exp_f32_e32 v63, v63
	v_lshlrev_b32_e32 v106, 16, v156
	v_and_b32_e32 v107, 0xffff0000, v156
	v_lshlrev_b32_e32 v115, 16, v157
	v_mul_f32_e32 v60, v60, v106
	v_and_b32_e32 v116, 0xffff0000, v157
	v_mul_f32_e32 v117, v117, v106
	v_mul_f32_e32 v118, v118, v107
	v_mul_f32_e32 v62, v62, v115
	v_cvt_pk_bf16_f32 v115, v117, v118
	ds_write_b32 v69, v115 offset:1632
	v_mul_f32_e32 v61, v61, v107
	v_cvt_pk_bf16_f32 v60, v60, v61
	v_mul_f32_e32 v63, v63, v116
	ds_write_b32 v69, v60 offset:19040
	v_cvt_pk_bf16_f32 v60, v62, v63
	v_pk_add_f32 v[58:59], v[104:105], v[58:59]
	ds_write_b32 v69, v60 offset:36448
	v_pk_add_f32 v[60:61], v[58:59], v[70:71] neg_lo:[0,1] neg_hi:[0,1]
	v_exp_f32_e32 v58, v58
	v_min_f32_e32 v106, 0x42e60000, v60
	v_min_f32_e32 v107, 0x42e60000, v61
	v_min_f32_e64 v60, -v60, s14
	v_exp_f32_e32 v106, v106
	v_exp_f32_e32 v107, v107
	v_exp_f32_e32 v60, v60
	v_min_f32_e64 v61, -v61, s14
	v_exp_f32_e32 v59, v59
	v_exp_f32_e32 v61, v61
	v_lshlrev_b32_e32 v70, 16, v158
	v_and_b32_e32 v71, 0xffff0000, v158
	v_lshlrev_b32_e32 v104, 16, v159
	v_mul_f32_e32 v58, v58, v70
	v_and_b32_e32 v105, 0xffff0000, v159
	v_mul_f32_e32 v106, v106, v70
	v_mul_f32_e32 v107, v107, v71
	v_mul_f32_e32 v60, v60, v104
	v_cvt_pk_bf16_f32 v104, v106, v107
	ds_write_b32 v69, v104 offset:1904
	v_mul_f32_e32 v59, v59, v71
	v_cvt_pk_bf16_f32 v58, v58, v59
	v_mul_f32_e32 v61, v61, v105
	ds_write_b32 v69, v58 offset:19312
	v_cvt_pk_bf16_f32 v58, v60, v61
	ds_write_b32 v69, v58 offset:36720
	v_cvt_pk_bf16_f32 v58, v66, v68
	v_mul_f32_e32 v62, v64, v62
	v_mul_f32_e32 v63, v63, v65
	v_mul_f32_e32 v64, v64, v60
	v_mul_f32_e32 v65, v61, v65
	v_cvt_pk_bf16_f32 v59, v73, v112
	v_cvt_pk_bf16_f32 v60, v110, v108
	v_cvt_pk_bf16_f32 v61, v62, v64
	ds_write_b128 v143, v[58:61] offset:52224
	v_cvt_pk_bf16_f32 v58, v67, v72
	s_add_i32 s3, s2, 1
	v_cvt_pk_bf16_f32 v59, v114, v113
	v_cvt_pk_bf16_f32 v60, v111, v109
	v_cvt_pk_bf16_f32 v61, v63, v65
	ds_write_b128 v143, v[58:61] offset:52368
	v_add_u32_e32 v58, s19, v74
	s_cmp_eq_u32 s2, 31
	ds_write_b16 v58, v22
	ds_write_b16_d16_hi v58, v22 offset:144
	ds_write_b16 v58, v23 offset:288
	ds_write_b16_d16_hi v58, v23 offset:432
	ds_write_b16 v58, v24 offset:576
	ds_write_b16_d16_hi v58, v24 offset:720
	ds_write_b16 v58, v25 offset:864
	ds_write_b16_d16_hi v58, v25 offset:1008
	s_waitcnt vmcnt(12)
	ds_write_b16 v58, v26 offset:1152
	ds_write_b16_d16_hi v58, v26 offset:1296
	ds_write_b16 v58, v27 offset:1440
	ds_write_b16_d16_hi v58, v27 offset:1584
	ds_write_b16 v58, v28 offset:1728
	ds_write_b16_d16_hi v58, v28 offset:1872
	ds_write_b16 v58, v29 offset:2016
	ds_write_b16_d16_hi v58, v29 offset:2160
	s_cbranch_scc1 .LBB0_1175
	s_lshl_b32 s6, s3, 6
	s_mov_b32 s7, s37
	s_lshl_b64 s[8:9], s[6:7], 13
	v_mad_u64_u32 v[24:25], s[8:9], s6, v204, v[78:79]
	s_or_b32 s8, s6, 1
	s_mov_b32 s9, s37
	v_add_co_u32_e32 v26, vcc, 0x1000, v24
	s_lshl_b64 s[10:11], s[8:9], 13
	s_nop 0
	v_addc_co_u32_e32 v27, vcc, 0, v25, vcc
	global_load_dword v75, v[24:25], off nt
	global_load_dword v125, v[26:27], off nt
	v_mad_u64_u32 v[22:23], s[8:9], s8, v204, v[78:79]
	v_add_co_u32_e32 v24, vcc, 0x1000, v22
	s_or_b32 s8, s6, 2
	s_mov_b32 s9, s37
	v_addc_co_u32_e32 v25, vcc, 0, v23, vcc
	s_lshl_b64 s[10:11], s[8:9], 13
	v_mad_u64_u32 v[28:29], s[8:9], s8, v204, v[78:79]
	v_add_co_u32_e32 v58, vcc, 0x1000, v28
	s_or_b32 s8, s6, 3
	s_mov_b32 s9, s37
	v_addc_co_u32_e32 v59, vcc, 0, v29, vcc
	global_load_dword v126, v[22:23], off nt
	global_load_dword v127, v[24:25], off nt
	global_load_dword v128, v[28:29], off nt
	global_load_dword v129, v[58:59], off nt
	s_lshl_b64 s[10:11], s[8:9], 13
	v_mad_u64_u32 v[24:25], s[8:9], s8, v204, v[78:79]
	s_or_b32 s8, s6, 4
	s_mov_b32 s9, s37
	v_add_co_u32_e32 v26, vcc, 0x1000, v24
	s_lshl_b64 s[10:11], s[8:9], 13
	s_nop 0
	v_addc_co_u32_e32 v27, vcc, 0, v25, vcc
	global_load_dword v130, v[24:25], off nt
	global_load_dword v131, v[26:27], off nt
	v_mad_u64_u32 v[22:23], s[8:9], s8, v204, v[78:79]
	v_add_co_u32_e32 v24, vcc, 0x1000, v22
	s_or_b32 s8, s6, 5
	s_mov_b32 s9, s37
	v_addc_co_u32_e32 v25, vcc, 0, v23, vcc
	s_lshl_b64 s[10:11], s[8:9], 13
	v_mad_u64_u32 v[28:29], s[8:9], s8, v204, v[78:79]
	v_add_co_u32_e32 v58, vcc, 0x1000, v28
	s_or_b32 s8, s6, 6
	s_mov_b32 s9, s37
	v_addc_co_u32_e32 v59, vcc, 0, v29, vcc
	global_load_dword v140, v[22:23], off nt
	global_load_dword v142, v[24:25], off nt
	global_load_dword v144, v[28:29], off nt
	global_load_dword v149, v[58:59], off nt
	s_lshl_b64 s[10:11], s[8:9], 13
	v_mad_u64_u32 v[24:25], s[8:9], s8, v204, v[78:79]
	s_or_b32 s6, s6, 7
	v_add_co_u32_e32 v26, vcc, 0x1000, v24
	s_lshl_b64 s[8:9], s[6:7], 13
	s_nop 0
	v_addc_co_u32_e32 v27, vcc, 0, v25, vcc
	global_load_dword v156, v[24:25], off nt
	global_load_dword v157, v[26:27], off nt
	v_mad_u64_u32 v[22:23], s[6:7], s6, v204, v[78:79]
	v_add_co_u32_e32 v24, vcc, 0x1000, v22
	s_mul_i32 s6, s3, 0x180000
	s_mov_b32 s7, s37
	v_addc_co_u32_e32 v25, vcc, 0, v23, vcc
	v_lshl_add_u64 v[26:27], v[84:85], 0, s[6:7]
	global_load_dword v158, v[22:23], off nt
	global_load_dword v159, v[24:25], off nt
	s_nop 0
	global_load_dwordx4 v[22:25], v[26:27], off
	s_nop 0
	global_load_dwordx4 v[26:29], v[26:27], off offset:16
